# v010 + P4 branch-projection phase start staggered by (blockIdx&7) x ~1.5us
# speedup vs baseline: 1.0227x; 1.0042x over previous
;     __device__ void init(int G_, int c_) { so.init(16384, 12288, G_, c_); G = G_; c = c_; }
;     __device__ bool next(int i, Unit& o) const { if (i != 0) return false; o = u; return true; }
;     __host__ __device__ bool next(int i, Unit& u) const {
;         const long L = (long)i * G + c; if (L >= nwg) return false;
;         int wgid = (int)L; { const int q = nwg / NXCD, r = nwg % NXCD, xcd = wgid % NXCD, off = wgid / NXCD; wgid = (xcd < r ? xcd * (q + 1) : r * (q + 1) + (xcd - r) * q) + off; }
;         const int nig = WGM * nN, gid = wgid / nig, fm = gid * WGM, gsz = (nM - fm) < WGM ? (nM - fm) : WGM;
;         u.pm = fm + ((wgid % nig) % gsz); u.pn = (wgid % nig) / gsz; return true;
; __global__ void __launch_bounds__(512, 2) fwd_megakernel(Params p_unused) {
;     ...
;   PHASE_BEGIN() WSP(ATT, WS_ATT); WSP(RG, WS_RG); WSP(WBA, WS_WBA); WSP(WBR, WS_WBR); WSP(Y, WS_Y); u16* T = (u16*)(ws + WS_T); u16* GATES = (u16*)p.out;
;   {
;     pg8::StaticOrder S; S.init(MTOK, DM, G, bx);
;     { pg8::Gemm g{ATT, WBA, MTOK, DM, 1024, 1024}; pg8::EpiMergeA E{GATES, T}; pg8::gemm_phase<pg8::EpiMergeA, pg8::StaticOrder, true, true>(glds, g, S, E); }
.LBB0_508:
	s_or_b64 exec, exec, s[4:5]
	s_cmpk_lt_i32 s96, 0x200
	s_cselect_b64 s[14:15], -1, 0
	s_lshr_b32 s0, s81, 29
	s_add_i32 s0, s96, s0
	s_ashr_i32 s57, s0, 3
	s_and_b32 s2, s0, -8
	s_mov_b64 s[0:1], s[86:87]
	s_waitcnt lgkmcnt(0)
	s_barrier
	s_and_b32 s98, s96, 7
	s_cbranch_scc0 .Lskew_p4_done

; DI unsigned cvtpk(float lo, float hi) { f32x2 v = {lo, hi}; bf16x2_t b = __builtin_convertvector(v, bf16x2_t); return __builtin_bit_cast(unsigned, b); }
; #define PG8_LAS __attribute__((address_space(3)))
; #define PG8_WAIT_V(n) asm volatile("s_waitcnt vmcnt(" #n ")" ::: "memory")
; #define PG8_BAR __builtin_amdgcn_s_barrier()
;     __device__ bool next(int i, Unit& o) const { if (i != 0) return false; o = u; return true; }
;     __host__ __device__ bool next(int i, Unit& u) const {
;         const long L = (long)i * G + c; if (L >= nwg) return false;
;         int wgid = (int)L; { const int q = nwg / NXCD, r = nwg % NXCD, xcd = wgid % NXCD, off = wgid / NXCD; wgid = (xcd < r ? xcd * (q + 1) : r * (q + 1) + (xcd - r) * q) + off; }
;         const int nig = WGM * nN, gid = wgid / nig, fm = gid * WGM, gsz = (nM - fm) < WGM ? (nM - fm) : WGM;
;         u.pm = fm + ((wgid % nig) % gsz); u.pn = (wgid % nig) / gsz; return true;
;     }
; __device__ __forceinline__ unsigned cvt_pk_bf16(float lo, float hi) { return cvtpk(lo, hi); }
; template <class Epi, class Sched, bool ALIGN_EPI = false, bool SP2 = false>
; __device__ __forceinline__ void gemm_phase(PG8_LAS unsigned char* lds, const Gemm g, const Sched& S, const Epi& E) {
;     int tid_ = threadIdx.x; asm volatile("" : "+v"(tid_)); const int tid = tid_, wid = __builtin_amdgcn_readfirstlane(tid >> 6), lane = tid & 63, wr = wid >> 2, wc = wid & 3, fr = lane & 15, fq = lane >> 4;
;     const int K = g.K, nt = K / BK;
;     unsigned voffA[2], voffB[2];
; #pragma unroll
;     for (int i = 0; i < 2; ++i) { int R, C; stage_rc(tid * 16 + i * 8192, R, C); const int Rb = Epi::PERM ? ((R & ~31) + perm32(R & 31)) : R;
;         voffA[i] = (unsigned)(R * g.lda + C) * 2u; voffB[i] = (unsigned)(Rb * K + C) * 2u; }
;     ...
;     const char* cA = (const char*)g.A + (size_t)cur.pm * tstepA; const char* cB = (const char*)g.Bt + (size_t)cur.pn * tstepB;
;     S.a_ready(cur);
;     if constexpr (SP2) {
;         PG8_STAGE(PG8_SB(0, 0), cB, voffB); PG8_STAGE(PG8_SB(0, 1), cB + hstepB, voffB); PG8_STAGE(PG8_SA(0, 0), cA, voffA); PG8_STAGE(PG8_SA(0, 1), cA + hstepA, voffA);
;         if (wr == 1) PG8_BAR;
;         PG8_WAIT_V(2); PG8_BAR;
;         PG8_STAGE(PG8_SB(1, 0), cB + kstep, voffB); PG8_STAGE(PG8_SA(1, 0), cA + kstep, voffA); PG8_STAGE(PG8_SB(1, 1), cB + hstepB + kstep, voffB);
;         PG8_WAIT_V(6); PG8_BAR;
.Lskew_p4_done:
	s_load_dwordx4 s[8:11], s[0:1], 0xc0
	s_sub_i32 s59, s96, s2
	s_cmp_lt_i32 s59, 0
	s_cselect_b64 s[12:13], -1, 0
	s_lshl_b32 s58, s59, 6
	s_waitcnt lgkmcnt(0)
	s_add_u32 s16, s10, 0xcc00000
	s_addc_u32 s17, s11, 0
	v_mov_b32_e32 v0, v194
	v_mov_b32_e32 v9, v194
	s_cmpk_gt_i32 s96, 0x1ff
	s_mulk_i32 s59, 0x41
	s_nop 0
	v_readfirstlane_b32 s5, v9
	s_cbranch_scc1 .LBB0_528
	v_lshlrev_b32_e32 v0, 4, v9
	v_add_u32_e32 v1, 0x2000, v0
	v_ashrrev_i32_e32 v2, 31, v1
	v_lshrrev_b32_e32 v2, 22, v2
	v_add_u32_e32 v2, v1, v2
	v_ashrrev_i32_e32 v8, 10, v2
	v_mul_i32_i24_e32 v2, 0x400, v8
	v_sub_u32_e32 v1, v1, v2
	v_lshrrev_b32_e32 v2, 4, v1
	v_bitop3_b32 v1, v2, v1, 32 bitop3:0x6c
	v_ashrrev_i32_e32 v2, 31, v1
	v_lshrrev_b32_e32 v2, 26, v2
	v_add_u32_e32 v2, v1, v2
	v_lshlrev_b32_e32 v3, 3, v8
	v_ashrrev_i32_e32 v10, 6, v2
	v_and_b32_e32 v3, -16, v3
	v_add_u32_e32 v3, v10, v3
	v_and_b32_e32 v4, 3, v10
	s_mov_b32 s4, 0x1fffe0
	v_lshrrev_b32_e32 v5, 2, v3
	v_lshlrev_b32_e32 v6, 1, v3
	v_and_b32_e32 v2, 0xc0, v2
	v_and_or_b32 v4, v3, s4, v4
	v_and_b32_e32 v5, 4, v5
	v_and_b32_e32 v6, 24, v6
	v_sub_u32_e32 v1, v1, v2
	v_mov_b32_e32 v2, 1
	v_or3_b32 v4, v4, v5, v6
	v_lshlrev_b32_e32 v5, 5, v8
	v_ashrrev_i16_sdwa v1, v2, sext(v1) dst_sel:DWORD dst_unused:UNUSED_PAD src0_sel:DWORD src1_sel:BYTE_0
	v_and_b32_e32 v5, 32, v5
	v_bfe_i32 v11, v1, 0, 16
	v_add_lshl_u32 v1, v5, v11, 1
	v_lshl_add_u32 v128, v4, 11, v1
	v_lshl_add_u32 v130, v3, 11, v1
	v_bfe_i32 v1, v9, 27, 1
	v_lshrrev_b32_e32 v1, 22, v1
	v_add_u32_e32 v1, v0, v1
	v_and_b32_e32 v1, 0xfffffc00, v1
	v_sub_u32_e32 v0, v0, v1
	v_lshrrev_b32_e32 v1, 4, v0
	v_ashrrev_i32_e32 v3, 31, v9
	s_add_u32 s0, s10, 0x4400000
	v_bitop3_b32 v0, v1, v0, 32 bitop3:0x6c
	v_lshrrev_b32_e32 v3, 26, v3
	s_addc_u32 s1, s11, 0
	v_ashrrev_i32_e32 v1, 31, v0
	v_add_u32_e32 v3, v9, v3
	s_add_u32 s2, s10, 0x7400000
	v_lshrrev_b32_e32 v1, 26, v1
	v_ashrrev_i32_e32 v13, 6, v3
	s_addc_u32 s3, s11, 0
	s_ashr_i32 s18, s5, 6
	v_add_u32_e32 v1, v0, v1
	v_lshlrev_b32_e32 v3, 3, v13
	s_ashr_i32 s20, s5, 8
	s_lshl_b32 s33, s18, 10
	v_ashrrev_i32_e32 v12, 6, v1
	v_and_b32_e32 v3, -16, v3
	v_add_u32_e32 v3, v12, v3
	v_and_b32_e32 v4, 3, v12
	s_and_b64 s[6:7], s[12:13], exec
	v_and_or_b32 v4, v3, s4, v4
	s_cselect_b32 s4, s59, s58
	s_add_i32 s4, s4, s57
	s_ashr_i32 s6, s4, 31
	s_lshr_b32 s6, s6, 27
	s_add_i32 s6, s4, s6
	s_ashr_i32 s7, s6, 5
	s_and_b32 s6, s6, 0xffe0
	s_sub_i32 s6, s4, s6
	s_bfe_i32 s4, s6, 0x80000
	s_bfe_u32 s4, s4, 0x2000d
	s_add_i32 s19, s6, s4
	s_bfe_i32 s4, s19, 0x80000
	s_and_b32 s19, s19, 0xfc
	s_sub_i32 s6, s6, s19
	s_lshl_b32 s7, s7, 2
	s_sext_i32_i16 s4, s4
	s_sext_i32_i8 s6, s6
	v_lshrrev_b32_e32 v5, 2, v3
	v_lshlrev_b32_e32 v6, 1, v3
	v_and_b32_e32 v1, 0xc0, v1
	s_lshr_b32 s4, s4, 2
	s_add_i32 s30, s7, s6
	v_and_b32_e32 v5, 4, v5
	v_and_b32_e32 v6, 24, v6
	v_sub_u32_e32 v0, v0, v1
	s_ashr_i32 s31, s30, 31
	s_bfe_i64 s[22:23], s[4:5], 0x100000
	v_or3_b32 v4, v4, v5, v6
	v_lshlrev_b32_e32 v5, 5, v13
	v_ashrrev_i16_sdwa v0, v2, sext(v0) dst_sel:DWORD dst_unused:UNUSED_PAD src0_sel:DWORD src1_sel:BYTE_0
	s_lshl_b64 s[6:7], s[30:31], 19
	s_lshl_b64 s[22:23], s[22:23], 19
	v_and_b32_e32 v5, 32, v5
	v_bfe_i32 v14, v0, 0, 16
	s_add_u32 s36, s2, s22
	v_add_lshl_u32 v0, v5, v14, 1
	s_addc_u32 s37, s3, s23
	s_add_i32 s31, s33, 0
	v_lshl_add_u32 v132, v4, 11, v0
	s_add_i32 m0, s31, 0x10000
	v_lshl_add_u32 v134, v3, 11, v0
	global_load_lds_dwordx4 v132, s[36:37]
	s_add_i32 m0, s31, 0x12000
	s_add_u32 s22, s36, 0x40000
	global_load_lds_dwordx4 v128, s[36:37]
	s_addc_u32 s23, s37, 0
	s_add_i32 m0, s31, 0x14000
	v_mov_b32_e32 v133, 0
	global_load_lds_dwordx4 v132, s[22:23]
	s_add_i32 m0, s31, 0x16000
	s_add_u32 s34, s0, s6
	s_addc_u32 s35, s1, s7
	s_add_i32 s40, s31, 0x2000
	global_load_lds_dwordx4 v128, s[22:23]
	s_mov_b32 m0, s31
	s_add_u32 s6, s34, 0x40000
	global_load_lds_dwordx4 v134, s[34:35]
	s_mov_b32 m0, s40
	s_addc_u32 s7, s35, 0
	s_add_i32 s41, s31, 0x4000
	global_load_lds_dwordx4 v130, s[34:35]
	s_mov_b32 m0, s41
	s_add_i32 s42, s31, 0x6000
	global_load_lds_dwordx4 v134, s[6:7]
	s_mov_b32 m0, s42
	v_mov_b32_e32 v129, v133
	global_load_lds_dwordx4 v130, s[6:7]
	v_mov_b32_e32 v135, v133
	v_mov_b32_e32 v131, v133
	s_cmp_eq_u32 s20, 1
	v_lshl_add_u64 v[6:7], s[36:37], 0, v[132:133]
	v_lshl_add_u64 v[4:5], s[36:37], 0, v[128:129]
	v_lshl_add_u64 v[0:1], s[34:35], 0, v[134:135]
	s_cselect_b64 s[6:7], -1, 0
	s_cmp_lg_u32 s20, 1
	v_lshl_add_u64 v[2:3], s[34:35], 0, v[130:131]
	s_cbranch_scc1 .LBB0_511
	s_barrier
